# P2b: CUM (f16) via LDS: pass B writes the f32 running sum back into the la tile, then 4 dwordx4 stores per thread replace 32 two-byte stores per thread and half-head
# speedup vs baseline: 1.0010x; 1.0010x over previous
.LBB0_286:
	s_add_i32 s5, s4, 0
	s_add_i32 s0, s5, 0x20400
	v_mov_b32_e32 v58, s0
	ds_read_b128 v[58:61], v58
	s_add_i32 s0, s5, 0x20410
	v_add_u32_e32 v74, 0, v0
	s_addk_i32 s4, 0x100
	s_add_i32 s2, s2, -4
	s_waitcnt vmcnt(5) lgkmcnt(0)
	v_pk_fma_f32 v[72:73], v[20:21], v[58:59], v[54:55] op_sel_hi:[1,0,1]
	v_add_u32_e32 v0, 0x800, v0
	v_pk_fma_f32 v[58:59], v[24:25], v[58:59], v[72:73] op_sel:[0,1,0]
	s_nop 0
	v_pk_fma_f32 v[58:59], v[26:27], v[60:61], v[58:59] op_sel_hi:[1,0,1]
	v_mov_b32_e32 v60, v61
	v_pk_fma_f32 v[72:73], v[28:29], v[60:61], v[58:59] op_sel_hi:[1,0,1]
	v_mov_b32_e32 v58, s0
	ds_read_b128 v[58:61], v58
	s_add_i32 s0, s5, 0x20420
	s_waitcnt lgkmcnt(0)
	v_pk_fma_f32 v[72:73], v[30:31], v[58:59], v[72:73] op_sel_hi:[1,0,1]
	s_nop 0
	v_pk_fma_f32 v[58:59], v[32:33], v[58:59], v[72:73] op_sel:[0,1,0]
	s_nop 0
	v_pk_fma_f32 v[58:59], v[34:35], v[60:61], v[58:59] op_sel_hi:[1,0,1]
	v_mov_b32_e32 v60, v61
	v_pk_fma_f32 v[72:73], v[36:37], v[60:61], v[58:59] op_sel_hi:[1,0,1]
	v_mov_b32_e32 v58, s0
	ds_read_b128 v[58:61], v58
	s_add_i32 s0, s5, 0x20430
	s_waitcnt lgkmcnt(0)
	v_pk_fma_f32 v[72:73], v[38:39], v[58:59], v[72:73] op_sel_hi:[1,0,1]
	s_nop 0
	v_pk_fma_f32 v[58:59], v[40:41], v[58:59], v[72:73] op_sel:[0,1,0]
	s_nop 0
	v_pk_fma_f32 v[58:59], v[42:43], v[60:61], v[58:59] op_sel_hi:[1,0,1]
	v_mov_b32_e32 v60, v61
	s_waitcnt vmcnt(4)
	v_pk_fma_f32 v[72:73], v[44:45], v[60:61], v[58:59] op_sel_hi:[1,0,1]
	v_mov_b32_e32 v58, s0
	ds_read_b128 v[58:61], v58
	s_waitcnt vmcnt(3) lgkmcnt(0)
	v_pk_fma_f32 v[72:73], v[46:47], v[58:59], v[72:73] op_sel_hi:[1,0,1]
	s_waitcnt vmcnt(2)
	v_pk_fma_f32 v[58:59], v[48:49], v[58:59], v[72:73] op_sel:[0,1,0]
	s_waitcnt vmcnt(1)
	v_pk_fma_f32 v[58:59], v[50:51], v[60:61], v[58:59] op_sel_hi:[1,0,1]
	v_mov_b32_e32 v60, v61
	s_waitcnt vmcnt(0)
	v_pk_fma_f32 v[58:59], v[52:53], v[60:61], v[58:59] op_sel_hi:[1,0,1]
	s_nop 0
	v_min_f32_e32 v60, 0, v58
	v_mul_f32_e64 v58, |v58|, s59
	v_exp_f32_e32 v58, v58
	s_nop 0
	v_add_f32_e32 v58, 1.0, v58
	v_cmp_gt_f32_e32 vcc, s3, v58
	s_nop 1
	v_cndmask_b32_e64 v61, 0, 32, vcc
	v_ldexp_f32 v58, v58, v61
	v_log_f32_e32 v58, v58
	s_nop 0
	v_mul_f32_e32 v61, 0x3f317217, v58
	v_fma_f32 v61, v58, s33, -v61
	v_fmac_f32_e32 v61, 0x3377d1cf, v58
	v_fmac_f32_e32 v61, 0x3f317217, v58
	v_cmp_lt_f32_e64 s[0:1], |v58|, s88
	s_nop 1
	v_cndmask_b32_e64 v58, v58, v61, s[0:1]
	v_cndmask_b32_e32 v61, 0, v169, vcc
	v_sub_f32_e32 v58, v58, v61
	v_min_f32_e32 v61, 0, v59
	v_mul_f32_e64 v59, |v59|, s59
	v_exp_f32_e32 v59, v59
	s_nop 0
	v_add_f32_e32 v59, 1.0, v59
	v_cmp_gt_f32_e32 vcc, s3, v59
	s_nop 1
	v_cndmask_b32_e64 v72, 0, 32, vcc
	v_ldexp_f32 v59, v59, v72
	v_log_f32_e32 v59, v59
	s_nop 0
	v_mul_f32_e32 v72, 0x3f317217, v59
	v_fma_f32 v72, v59, s33, -v72
	v_fmac_f32_e32 v72, 0x3377d1cf, v59
	v_fmac_f32_e32 v72, 0x3f317217, v59
	v_cmp_lt_f32_e64 s[0:1], |v59|, s88
	s_nop 1
	v_cndmask_b32_e64 v59, v59, v72, s[0:1]
	v_cndmask_b32_e32 v72, 0, v169, vcc
	v_sub_f32_e32 v59, v59, v72
	v_pk_add_f32 v[58:59], v[60:61], v[58:59] neg_lo:[0,1] neg_hi:[0,1]
	v_add_u32_e32 v72, 0x10000, v74
	v_pk_mul_f32 v[60:61], v[58:59], s[26:27] op_sel_hi:[1,0]
	s_add_i32 s0, s5, 0x20440
	ds_write_b64 v72, v[60:61]
	v_pk_fma_f32 v[60:61], v[58:59], s[26:27], v[56:57] op_sel_hi:[1,0,1]
	v_mov_b32_e32 v56, s0
	ds_read_b128 v[56:59], v56
	s_add_i32 s0, s5, 0x20450
	s_waitcnt lgkmcnt(0)
	v_pk_fma_f32 v[72:73], v[20:21], v[56:57], v[54:55] op_sel_hi:[1,0,1]
	s_nop 0
	v_pk_fma_f32 v[56:57], v[24:25], v[56:57], v[72:73] op_sel:[0,1,0]
	s_nop 0
	v_pk_fma_f32 v[56:57], v[26:27], v[58:59], v[56:57] op_sel_hi:[1,0,1]
	v_mov_b32_e32 v58, v59
	v_pk_fma_f32 v[72:73], v[28:29], v[58:59], v[56:57] op_sel_hi:[1,0,1]
	v_mov_b32_e32 v56, s0
	ds_read_b128 v[56:59], v56
	s_add_i32 s0, s5, 0x20460
	s_waitcnt lgkmcnt(0)
	v_pk_fma_f32 v[72:73], v[30:31], v[56:57], v[72:73] op_sel_hi:[1,0,1]
	s_nop 0
	v_pk_fma_f32 v[56:57], v[32:33], v[56:57], v[72:73] op_sel:[0,1,0]
	s_nop 0
	v_pk_fma_f32 v[56:57], v[34:35], v[58:59], v[56:57] op_sel_hi:[1,0,1]
	v_mov_b32_e32 v58, v59
	v_pk_fma_f32 v[72:73], v[36:37], v[58:59], v[56:57] op_sel_hi:[1,0,1]
	v_mov_b32_e32 v56, s0
	ds_read_b128 v[56:59], v56
	s_add_i32 s0, s5, 0x20470
	s_waitcnt lgkmcnt(0)
	v_pk_fma_f32 v[72:73], v[38:39], v[56:57], v[72:73] op_sel_hi:[1,0,1]
	s_nop 0
	v_pk_fma_f32 v[56:57], v[40:41], v[56:57], v[72:73] op_sel:[0,1,0]
	s_nop 0
	v_pk_fma_f32 v[56:57], v[42:43], v[58:59], v[56:57] op_sel_hi:[1,0,1]
	v_mov_b32_e32 v58, v59
	v_pk_fma_f32 v[72:73], v[44:45], v[58:59], v[56:57] op_sel_hi:[1,0,1]
	v_mov_b32_e32 v56, s0
	ds_read_b128 v[56:59], v56
	s_waitcnt lgkmcnt(0)
	v_pk_fma_f32 v[72:73], v[46:47], v[56:57], v[72:73] op_sel_hi:[1,0,1]
	s_nop 0
	v_pk_fma_f32 v[56:57], v[48:49], v[56:57], v[72:73] op_sel:[0,1,0]
	s_nop 0
	v_pk_fma_f32 v[56:57], v[50:51], v[58:59], v[56:57] op_sel_hi:[1,0,1]
	v_mov_b32_e32 v58, v59
	v_pk_fma_f32 v[56:57], v[52:53], v[58:59], v[56:57] op_sel_hi:[1,0,1]
	s_nop 0
	v_min_f32_e32 v58, 0, v56
	v_mul_f32_e64 v56, |v56|, s59
	v_exp_f32_e32 v56, v56
	s_nop 0
	v_add_f32_e32 v56, 1.0, v56
	v_cmp_gt_f32_e32 vcc, s3, v56
	s_nop 1
	v_cndmask_b32_e64 v59, 0, 32, vcc
	v_ldexp_f32 v56, v56, v59
	v_log_f32_e32 v56, v56
	s_nop 0
	v_mul_f32_e32 v59, 0x3f317217, v56
	v_fma_f32 v59, v56, s33, -v59
	v_fmac_f32_e32 v59, 0x3377d1cf, v56
	v_fmac_f32_e32 v59, 0x3f317217, v56
	v_cmp_lt_f32_e64 s[0:1], |v56|, s88
	s_nop 1
	v_cndmask_b32_e64 v56, v56, v59, s[0:1]
	v_cndmask_b32_e32 v59, 0, v169, vcc
	v_sub_f32_e32 v56, v56, v59
	v_min_f32_e32 v59, 0, v57
	v_mul_f32_e64 v57, |v57|, s59
	v_exp_f32_e32 v57, v57
	s_nop 0
	v_add_f32_e32 v57, 1.0, v57
	v_cmp_gt_f32_e32 vcc, s3, v57
	s_nop 1
	v_cndmask_b32_e64 v72, 0, 32, vcc
	v_ldexp_f32 v57, v57, v72
	v_log_f32_e32 v57, v57
	s_nop 0
	v_mul_f32_e32 v72, 0x3f317217, v57
	v_fma_f32 v72, v57, s33, -v72
	v_fmac_f32_e32 v72, 0x3377d1cf, v57
	v_fmac_f32_e32 v72, 0x3f317217, v57
	v_cmp_lt_f32_e64 s[0:1], |v57|, s88
	s_nop 1
	v_cndmask_b32_e64 v57, v57, v72, s[0:1]
	v_cndmask_b32_e32 v72, 0, v169, vcc
	v_sub_f32_e32 v57, v57, v72
	v_pk_add_f32 v[56:57], v[58:59], v[56:57] neg_lo:[0,1] neg_hi:[0,1]
	v_add_u32_e32 v72, 0x10200, v74
	v_pk_mul_f32 v[58:59], v[56:57], s[26:27] op_sel_hi:[1,0]
	s_add_i32 s0, s5, 0x20480
	ds_write_b64 v72, v[58:59]
	v_pk_fma_f32 v[60:61], v[56:57], s[26:27], v[60:61] op_sel_hi:[1,0,1]
	v_mov_b32_e32 v56, s0
	ds_read_b128 v[56:59], v56
	s_add_i32 s0, s5, 0x20490
	s_waitcnt lgkmcnt(0)
	v_pk_fma_f32 v[72:73], v[20:21], v[56:57], v[54:55] op_sel_hi:[1,0,1]
	s_nop 0
	v_pk_fma_f32 v[56:57], v[24:25], v[56:57], v[72:73] op_sel:[0,1,0]
	s_nop 0
	v_pk_fma_f32 v[56:57], v[26:27], v[58:59], v[56:57] op_sel_hi:[1,0,1]
	v_mov_b32_e32 v58, v59
	v_pk_fma_f32 v[72:73], v[28:29], v[58:59], v[56:57] op_sel_hi:[1,0,1]
	v_mov_b32_e32 v56, s0
	ds_read_b128 v[56:59], v56
	s_add_i32 s0, s5, 0x204a0
	s_waitcnt lgkmcnt(0)
	v_pk_fma_f32 v[72:73], v[30:31], v[56:57], v[72:73] op_sel_hi:[1,0,1]
	s_nop 0
	v_pk_fma_f32 v[56:57], v[32:33], v[56:57], v[72:73] op_sel:[0,1,0]
	s_nop 0
	v_pk_fma_f32 v[56:57], v[34:35], v[58:59], v[56:57] op_sel_hi:[1,0,1]
	v_mov_b32_e32 v58, v59
	v_pk_fma_f32 v[72:73], v[36:37], v[58:59], v[56:57] op_sel_hi:[1,0,1]
	v_mov_b32_e32 v56, s0
	ds_read_b128 v[56:59], v56
	s_add_i32 s0, s5, 0x204b0
	s_waitcnt lgkmcnt(0)
	v_pk_fma_f32 v[72:73], v[38:39], v[56:57], v[72:73] op_sel_hi:[1,0,1]
	s_nop 0
	v_pk_fma_f32 v[56:57], v[40:41], v[56:57], v[72:73] op_sel:[0,1,0]
	s_nop 0
	v_pk_fma_f32 v[56:57], v[42:43], v[58:59], v[56:57] op_sel_hi:[1,0,1]
	v_mov_b32_e32 v58, v59
	v_pk_fma_f32 v[72:73], v[44:45], v[58:59], v[56:57] op_sel_hi:[1,0,1]
	v_mov_b32_e32 v56, s0
	ds_read_b128 v[56:59], v56
	s_waitcnt lgkmcnt(0)
	v_pk_fma_f32 v[72:73], v[46:47], v[56:57], v[72:73] op_sel_hi:[1,0,1]
	s_nop 0
	v_pk_fma_f32 v[56:57], v[48:49], v[56:57], v[72:73] op_sel:[0,1,0]
	s_nop 0
	v_pk_fma_f32 v[56:57], v[50:51], v[58:59], v[56:57] op_sel_hi:[1,0,1]
	v_mov_b32_e32 v58, v59
	v_pk_fma_f32 v[56:57], v[52:53], v[58:59], v[56:57] op_sel_hi:[1,0,1]
	s_nop 0
	v_min_f32_e32 v58, 0, v56
	v_mul_f32_e64 v56, |v56|, s59
	v_exp_f32_e32 v56, v56
	s_nop 0
	v_add_f32_e32 v56, 1.0, v56
	v_cmp_gt_f32_e32 vcc, s3, v56
	s_nop 1
	v_cndmask_b32_e64 v59, 0, 32, vcc
	v_ldexp_f32 v56, v56, v59
	v_log_f32_e32 v56, v56
	s_nop 0
	v_mul_f32_e32 v59, 0x3f317217, v56
	v_fma_f32 v59, v56, s33, -v59
	v_fmac_f32_e32 v59, 0x3377d1cf, v56
	v_fmac_f32_e32 v59, 0x3f317217, v56
	v_cmp_lt_f32_e64 s[0:1], |v56|, s88
	s_nop 1
	v_cndmask_b32_e64 v56, v56, v59, s[0:1]
	v_cndmask_b32_e32 v59, 0, v169, vcc
	v_sub_f32_e32 v56, v56, v59
	v_min_f32_e32 v59, 0, v57
	v_mul_f32_e64 v57, |v57|, s59
	v_exp_f32_e32 v57, v57
	s_nop 0
	v_add_f32_e32 v57, 1.0, v57
	v_cmp_gt_f32_e32 vcc, s3, v57
	s_nop 1
	v_cndmask_b32_e64 v72, 0, 32, vcc
	v_ldexp_f32 v57, v57, v72
	v_log_f32_e32 v57, v57
	s_nop 0
	v_mul_f32_e32 v72, 0x3f317217, v57
	v_fma_f32 v72, v57, s33, -v72
	v_fmac_f32_e32 v72, 0x3377d1cf, v57
	v_fmac_f32_e32 v72, 0x3f317217, v57
	v_cmp_lt_f32_e64 s[0:1], |v57|, s88
	s_nop 1
	v_cndmask_b32_e64 v57, v57, v72, s[0:1]
	v_cndmask_b32_e32 v72, 0, v169, vcc
	v_sub_f32_e32 v57, v57, v72
	v_pk_add_f32 v[56:57], v[58:59], v[56:57] neg_lo:[0,1] neg_hi:[0,1]
	v_add_u32_e32 v72, 0x10400, v74
	v_pk_mul_f32 v[58:59], v[56:57], s[26:27] op_sel_hi:[1,0]
	s_add_i32 s0, s5, 0x204c0
	ds_write_b64 v72, v[58:59]
	v_pk_fma_f32 v[60:61], v[56:57], s[26:27], v[60:61] op_sel_hi:[1,0,1]
	v_mov_b32_e32 v56, s0
	ds_read_b128 v[56:59], v56
	s_add_i32 s0, s5, 0x204d0
	s_waitcnt lgkmcnt(0)
	v_pk_fma_f32 v[72:73], v[20:21], v[56:57], v[54:55] op_sel_hi:[1,0,1]
	s_nop 0
	v_pk_fma_f32 v[56:57], v[24:25], v[56:57], v[72:73] op_sel:[0,1,0]
	s_nop 0
	v_pk_fma_f32 v[56:57], v[26:27], v[58:59], v[56:57] op_sel_hi:[1,0,1]
	v_mov_b32_e32 v58, v59
	v_pk_fma_f32 v[72:73], v[28:29], v[58:59], v[56:57] op_sel_hi:[1,0,1]
	v_mov_b32_e32 v56, s0
	ds_read_b128 v[56:59], v56
	s_add_i32 s0, s5, 0x204e0
	s_waitcnt lgkmcnt(0)
	v_pk_fma_f32 v[72:73], v[30:31], v[56:57], v[72:73] op_sel_hi:[1,0,1]
	s_nop 0
	v_pk_fma_f32 v[56:57], v[32:33], v[56:57], v[72:73] op_sel:[0,1,0]
	s_nop 0
	v_pk_fma_f32 v[56:57], v[34:35], v[58:59], v[56:57] op_sel_hi:[1,0,1]
	v_mov_b32_e32 v58, v59
	v_pk_fma_f32 v[72:73], v[36:37], v[58:59], v[56:57] op_sel_hi:[1,0,1]
	v_mov_b32_e32 v56, s0
	ds_read_b128 v[56:59], v56
	s_add_i32 s0, s5, 0x204f0
	s_cmp_eq_u32 s2, 0
	s_waitcnt lgkmcnt(0)
	v_pk_fma_f32 v[72:73], v[38:39], v[56:57], v[72:73] op_sel_hi:[1,0,1]
	s_nop 0
	v_pk_fma_f32 v[56:57], v[40:41], v[56:57], v[72:73] op_sel:[0,1,0]
	s_nop 0
	v_pk_fma_f32 v[56:57], v[42:43], v[58:59], v[56:57] op_sel_hi:[1,0,1]
	v_mov_b32_e32 v58, v59
	v_pk_fma_f32 v[72:73], v[44:45], v[58:59], v[56:57] op_sel_hi:[1,0,1]
	v_mov_b32_e32 v56, s0
	ds_read_b128 v[56:59], v56
	s_waitcnt lgkmcnt(0)
	v_pk_fma_f32 v[72:73], v[46:47], v[56:57], v[72:73] op_sel_hi:[1,0,1]
	s_nop 0
	v_pk_fma_f32 v[56:57], v[48:49], v[56:57], v[72:73] op_sel:[0,1,0]
	s_nop 0
	v_pk_fma_f32 v[56:57], v[50:51], v[58:59], v[56:57] op_sel_hi:[1,0,1]
	v_mov_b32_e32 v58, v59
	v_pk_fma_f32 v[56:57], v[52:53], v[58:59], v[56:57] op_sel_hi:[1,0,1]
	s_nop 0
	v_min_f32_e32 v58, 0, v56
	v_mul_f32_e64 v56, |v56|, s59
	v_exp_f32_e32 v56, v56
	s_nop 0
	v_add_f32_e32 v56, 1.0, v56
	v_cmp_gt_f32_e32 vcc, s3, v56
	s_nop 1
	v_cndmask_b32_e64 v59, 0, 32, vcc
	v_ldexp_f32 v56, v56, v59
	v_log_f32_e32 v56, v56
	s_nop 0
	v_mul_f32_e32 v59, 0x3f317217, v56
	v_fma_f32 v59, v56, s33, -v59
	v_fmac_f32_e32 v59, 0x3377d1cf, v56
	v_fmac_f32_e32 v59, 0x3f317217, v56
	v_cmp_lt_f32_e64 s[0:1], |v56|, s88
	s_nop 1
	v_cndmask_b32_e64 v56, v56, v59, s[0:1]
	v_cndmask_b32_e32 v59, 0, v169, vcc
	v_sub_f32_e32 v56, v56, v59
	v_min_f32_e32 v59, 0, v57
	v_mul_f32_e64 v57, |v57|, s59
	v_exp_f32_e32 v57, v57
	s_nop 0
	v_add_f32_e32 v57, 1.0, v57
	v_cmp_gt_f32_e32 vcc, s3, v57
	s_nop 1
	v_cndmask_b32_e64 v72, 0, 32, vcc
	v_ldexp_f32 v57, v57, v72
	v_log_f32_e32 v57, v57
	s_nop 0
	v_mul_f32_e32 v72, 0x3f317217, v57
	v_fma_f32 v72, v57, s33, -v72
	v_fmac_f32_e32 v72, 0x3377d1cf, v57
	v_fmac_f32_e32 v72, 0x3f317217, v57
	v_cmp_lt_f32_e64 s[0:1], |v57|, s88
	s_nop 1
	v_cndmask_b32_e64 v57, v57, v72, s[0:1]
	v_cndmask_b32_e32 v72, 0, v169, vcc
	v_sub_f32_e32 v57, v57, v72
	v_pk_add_f32 v[56:57], v[58:59], v[56:57] neg_lo:[0,1] neg_hi:[0,1]
	v_add_u32_e32 v72, 0x10600, v74
	v_pk_mul_f32 v[58:59], v[56:57], s[26:27] op_sel_hi:[1,0]
	v_pk_fma_f32 v[56:57], v[56:57], s[26:27], v[60:61] op_sel_hi:[1,0,1]
	ds_write_b64 v72, v[58:59]
	s_cbranch_scc0 .LBB0_286
	s_lshl_b32 s0, s46, 9
	v_readlane_b32 s2, v254, 27
	v_and_b32_e32 v0, 0x7f, v70
	s_add_i32 s0, s2, s0
	v_lshlrev_b32_e32 v29, 2, v0
	v_lshl_add_u32 v72, v71, 2, s0
	v_add_u32_e32 v71, s2, v29
	ds_write_b64 v72, v[56:57]
	s_waitcnt lgkmcnt(0)
	s_barrier
	ds_read2st64_b32 v[20:21], v71 offset1:2
	ds_read2st64_b32 v[24:25], v71 offset0:4 offset1:6
	v_ashrrev_i32_e32 v30, 7, v70
	v_cmp_lt_i32_e64 s[44:45], 0, v30
	v_cmp_lt_i32_e64 s[42:43], 1, v30
	s_waitcnt lgkmcnt(1)
	v_add_f32_e32 v20, 0, v20
	v_add_f32_e32 v20, v20, v21
	v_cndmask_b32_e64 v26, 0, v20, s[44:45]
	s_waitcnt lgkmcnt(0)
	v_add_f32_e32 v27, v20, v24
	ds_read2st64_b32 v[20:21], v71 offset0:8 offset1:10
	v_add_f32_e32 v24, v24, v26
	v_add_f32_e32 v24, v25, v24
	v_add_f32_e32 v27, v27, v25
	v_cndmask_b32_e64 v26, v26, v24, s[42:43]
	ds_read2st64_b32 v[24:25], v71 offset0:12 offset1:14
	s_waitcnt lgkmcnt(1)
	v_add_f32_e32 v27, v27, v20
	v_add_f32_e32 v20, v20, v26
	v_add_f32_e32 v20, v21, v20
	v_cmp_lt_i32_e64 s[40:41], 2, v30
	v_add_f32_e32 v27, v27, v21
	s_waitcnt lgkmcnt(0)
	v_add_f32_e32 v21, v27, v24
	v_cndmask_b32_e64 v20, v26, v20, s[40:41]
	v_add_f32_e32 v24, v24, v20
	s_and_b32 s1, s35, 0xffffff80
	v_add_f32_e32 v26, v21, v25
	v_add_f32_e32 v21, v25, v24
	v_cmp_lt_i32_e64 s[36:37], 3, v30
	s_and_b32 s49, s9, 3
	s_lshl_b32 s50, s49, 9
	v_cndmask_b32_e64 v28, v20, v21, s[36:37]
	v_lshl_add_u32 v20, v30, 5, s1
	v_ashrrev_i32_e32 v21, 31, v20
	v_lshlrev_b32_e32 v31, 1, v63
	v_lshlrev_b64 v[20:21], 11, v[20:21]
	v_lshlrev_b32_e32 v24, 1, v0
	v_lshlrev_b32_e32 v30, 14, v30
	v_or3_b32 v20, v20, s50, v24
	v_and_or_b32 v31, v31, 14, v30
	v_or_b32_e32 v29, v30, v29
	s_mov_b32 s0, 1
	v_bfe_u32 v27, v70, 3, 4
	v_lshl_add_u64 v[24:25], s[14:15], 0, v[20:21]
	s_nop 1
	v_readfirstlane_b32 s76, v24
	v_readfirstlane_b32 s77, v25
	v_readlane_b32 s78, v252, 8
	s_lshr_b32 s79, s78, 7
	s_lshl_b32 s79, s79, 16
	s_and_b32 s78, s78, 64
	s_lshl_b32 s78, s78, 1
	s_add_i32 s78, s78, s79
	s_addk_i32 s78, 0x3800
	s_sub_u32 s76, s76, s78
	s_subb_u32 s77, s77, 0
	v_add_u32_e32 v60, 0, v31
	v_add_u32_e32 v61, 0, v29
	s_movk_i32 s1, 0xc000
.LBB0_288:
	v_add_u32_e32 v30, s1, v61
	v_add_u32_e32 v211, 0x10000, v30
	v_add_u32_e32 v29, 0x14000, v30
	ds_read_b32 v29, v29
	s_add_i32 s2, s0, -1
	s_and_b32 s4, s2, 2
	s_waitcnt lgkmcnt(0)
	v_add_f32_e32 v31, v28, v29
	v_cvt_f16_f32_e32 v32, v31
	v_add_co_u32_e32 v28, vcc, 0xffffd000, v24
	v_sub_f32_e32 v34, v26, v31
	s_nop 0
	v_addc_co_u32_e32 v29, vcc, -1, v25, vcc
	ds_write_b32 v211, v31 offset:16384
	v_bitop3_b32 v32, s2, v27, 2 bitop3:0x6c
	v_lshlrev_b32_e32 v32, 4, v32
	v_add3_u32 v32, v60, v32, s1
	ds_read_u16 v33, v32 offset:16384
	v_mul_f32_e32 v34, 0x3fb8aa3b, v34
	v_exp_f32_e32 v34, v34
	s_and_b32 s2, s0, 3
	s_waitcnt lgkmcnt(0)
	v_lshlrev_b32_e32 v33, 16, v33
	v_mul_f32_e32 v33, v34, v33
	v_bfe_u32 v34, v33, 16, 1
	v_add3_u32 v33, v33, v34, s90
	ds_write_b16_d16_hi v32, v33 offset:16384
	v_add_u32_e32 v32, 0x14200, v30
	ds_read_b32 v32, v32
	s_waitcnt lgkmcnt(0)
	v_add_f32_e32 v31, v31, v32
	v_cvt_f16_f32_e32 v32, v31
	ds_write_b32 v211, v31 offset:16896
	v_bitop3_b32 v28, s4, v27, 4 bitop3:0x36
	v_lshlrev_b32_e32 v28, 4, v28
	v_add3_u32 v28, v60, v28, s1
	ds_read_u16 v29, v28 offset:16896
	v_sub_f32_e32 v32, v26, v31
	v_mul_f32_e32 v32, 0x3fb8aa3b, v32
	v_exp_f32_e32 v32, v32
	s_waitcnt lgkmcnt(0)
	v_lshlrev_b32_e32 v29, 16, v29
	v_mul_f32_e32 v29, v32, v29
	v_bfe_u32 v32, v29, 16, 1
	v_add3_u32 v29, v29, v32, s90
	ds_write_b16_d16_hi v28, v29 offset:16896
	v_add_u32_e32 v28, 0x14400, v30
	ds_read_b32 v28, v28
	s_waitcnt lgkmcnt(0)
	v_add_f32_e32 v31, v31, v28
	v_cvt_f16_f32_e32 v32, v31
	v_add_co_u32_e32 v28, vcc, s91, v24
	v_sub_f32_e32 v34, v26, v31
	s_nop 0
	v_addc_co_u32_e32 v29, vcc, -1, v25, vcc
	ds_write_b32 v211, v31 offset:17408
	v_bitop3_b32 v32, s4, v27, 8 bitop3:0x36
	v_lshlrev_b32_e32 v32, 4, v32
	v_add3_u32 v32, v60, v32, s1
	ds_read_u16 v33, v32 offset:17408
	v_mul_f32_e32 v34, 0x3fb8aa3b, v34
	v_exp_f32_e32 v34, v34
	s_waitcnt lgkmcnt(0)
	v_lshlrev_b32_e32 v33, 16, v33
	v_mul_f32_e32 v33, v34, v33
	v_bfe_u32 v34, v33, 16, 1
	v_add3_u32 v33, v33, v34, s90
	ds_write_b16_d16_hi v32, v33 offset:17408
	v_add_u32_e32 v32, 0x14600, v30
	ds_read_b32 v32, v32
	s_waitcnt lgkmcnt(0)
	v_add_f32_e32 v31, v31, v32
	v_cvt_f16_f32_e32 v32, v31
	ds_write_b32 v211, v31 offset:17920
	v_bitop3_b32 v28, s4, v27, 12 bitop3:0x36
	v_lshlrev_b32_e32 v28, 4, v28
	v_add3_u32 v28, v60, v28, s1
	ds_read_u16 v29, v28 offset:17920
	v_sub_f32_e32 v32, v26, v31
	v_mul_f32_e32 v32, 0x3fb8aa3b, v32
	v_exp_f32_e32 v32, v32
	s_waitcnt lgkmcnt(0)
	v_lshlrev_b32_e32 v29, 16, v29
	v_mul_f32_e32 v29, v32, v29
	v_bfe_u32 v32, v29, 16, 1
	v_add3_u32 v29, v29, v32, s90
	ds_write_b16_d16_hi v28, v29 offset:17920
	v_add_u32_e32 v28, 0x14800, v30
	ds_read_b32 v28, v28
	s_waitcnt lgkmcnt(0)
	v_add_f32_e32 v31, v31, v28
	v_cvt_f16_f32_e32 v32, v31
	v_add_co_u32_e32 v28, vcc, s92, v24
	s_nop 1
	v_addc_co_u32_e32 v29, vcc, -1, v25, vcc
	ds_write_b32 v211, v31 offset:18432
	v_bitop3_b32 v28, s0, v27, 3 bitop3:0x6c
	v_lshlrev_b32_e32 v28, 4, v28
	v_add3_u32 v28, v60, v28, s1
	ds_read_u16 v29, v28 offset:18432
	v_sub_f32_e32 v32, v26, v31
	v_mul_f32_e32 v32, 0x3fb8aa3b, v32
	v_exp_f32_e32 v32, v32
	s_add_i32 s0, s0, 2
	s_waitcnt lgkmcnt(0)
	v_lshlrev_b32_e32 v29, 16, v29
	v_mul_f32_e32 v29, v32, v29
	v_bfe_u32 v32, v29, 16, 1
	v_add3_u32 v29, v29, v32, s90
	ds_write_b16_d16_hi v28, v29 offset:18432
	v_add_u32_e32 v28, 0x14a00, v30
	ds_read_b32 v28, v28
	s_waitcnt lgkmcnt(0)
	v_add_f32_e32 v28, v31, v28
	v_cvt_f16_f32_e32 v29, v28
	v_sub_f32_e32 v32, v26, v28
	v_mul_f32_e32 v32, 0x3fb8aa3b, v32
	v_exp_f32_e32 v32, v32
	ds_write_b32 v211, v28 offset:18944
	v_bitop3_b32 v29, s2, v27, 4 bitop3:0x36
	v_lshlrev_b32_e32 v29, 4, v29
	v_add3_u32 v29, v60, v29, s1
	ds_read_u16 v31, v29 offset:18944
	s_waitcnt lgkmcnt(0)
	v_lshlrev_b32_e32 v31, 16, v31
	v_mul_f32_e32 v31, v32, v31
	v_bfe_u32 v32, v31, 16, 1
	v_add3_u32 v31, v31, v32, s90
	ds_write_b16_d16_hi v29, v31 offset:18944
	v_add_u32_e32 v29, 0x14c00, v30
	ds_read_b32 v29, v29
	s_waitcnt lgkmcnt(0)
	v_add_f32_e32 v28, v28, v29
	v_cvt_f16_f32_e32 v29, v28
	v_sub_f32_e32 v32, v26, v28
	v_mul_f32_e32 v32, 0x3fb8aa3b, v32
	v_exp_f32_e32 v32, v32
	ds_write_b32 v211, v28 offset:19456
	v_bitop3_b32 v29, s2, v27, 8 bitop3:0x36
	v_lshlrev_b32_e32 v29, 4, v29
	v_add3_u32 v29, v60, v29, s1
	ds_read_u16 v31, v29 offset:19456
	s_waitcnt lgkmcnt(0)
	v_lshlrev_b32_e32 v31, 16, v31
	v_mul_f32_e32 v31, v32, v31
	v_bfe_u32 v32, v31, 16, 1
	v_add3_u32 v31, v31, v32, s90
	ds_write_b16_d16_hi v29, v31 offset:19456
	v_add_u32_e32 v29, 0x14e00, v30
	ds_read_b32 v29, v29
	s_waitcnt lgkmcnt(0)
	v_add_f32_e32 v28, v28, v29
	v_cvt_f16_f32_e32 v29, v28
	v_sub_f32_e32 v31, v26, v28
	v_mul_f32_e32 v31, 0x3fb8aa3b, v31
	v_exp_f32_e32 v31, v31
	ds_write_b32 v211, v28 offset:19968
	v_bitop3_b32 v29, s2, v27, 12 bitop3:0x36
	v_lshlrev_b32_e32 v29, 4, v29
	v_add3_u32 v29, v60, v29, s1
	ds_read_u16 v30, v29 offset:19968
	s_addk_i32 s1, 0x1000
	v_lshl_add_u64 v[24:25], v[24:25], 0, s[66:67]
	s_cmp_eq_u32 s1, 0
	s_waitcnt lgkmcnt(0)
	v_lshlrev_b32_e32 v30, 16, v30
	v_mul_f32_e32 v30, v31, v30
	v_bfe_u32 v31, v30, 16, 1
	v_add3_u32 v30, v30, v31, s90
	ds_write_b16_d16_hi v29, v30 offset:19968
	s_cbranch_scc0 .LBB0_288
	s_movk_i32 s0, 0x80
	s_ashr_i32 s21, s20, 31
	v_cmp_gt_u32_e64 s[38:39], s0, v70
	s_lshl_b64 s[0:1], s[20:21], 10
	s_add_u32 s16, s7, s0
	s_addc_u32 s17, s8, s1
	v_lshlrev_b32_e32 v70, 2, v0
	s_and_saveexec_b64 s[0:1], s[38:39]
	s_cbranch_execz .LBB0_291
	v_mul_f32_e32 v24, 0x3fb8aa3b, v26
	v_exp_f32_e32 v24, v24
	global_store_dword v70, v24, s[16:17]
.LBB0_291:
	s_or_b64 exec, exec, s[0:1]
	s_waitcnt lgkmcnt(0)
	s_barrier
	v_mbcnt_lo_u32_b32 v58, -1, 0
	v_mbcnt_hi_u32_b32 v58, -1, v58
	v_readlane_b32 s78, v252, 8
	s_mov_b32 s79, 0xffff
	v_add_u32_e32 v58, s78, v58
	v_lshlrev_b32_e32 v56, 5, v58
	v_add_u32_e32 v56, 0x10000, v56
	ds_read_b128 v[24:27], v56 offset:0
	ds_read_b128 v[28:31], v56 offset:16
	ds_read_b128 v[32:35], v56 offset:16384
	ds_read_b128 v[36:39], v56 offset:16400
	ds_read_b128 v[40:43], v56 offset:32768
	ds_read_b128 v[44:47], v56 offset:32784
	ds_read_b128 v[48:51], v56 offset:49152
	ds_read_b128 v[52:55], v56 offset:49168
	v_lshrrev_b32_e32 v57, 4, v58
	v_lshlrev_b32_e32 v57, 11, v57
	v_and_b32_e32 v58, 15, v58
	v_lshl_add_u32 v57, v58, 4, v57
	s_waitcnt lgkmcnt(0)
	s_barrier
	v_cvt_f16_f32_e32 v24, v24
	v_cvt_f16_f32_e32 v25, v25
	v_cvt_f16_f32_e32 v26, v26
	v_cvt_f16_f32_e32 v27, v27
	v_cvt_f16_f32_e32 v28, v28
	v_cvt_f16_f32_e32 v29, v29
	v_cvt_f16_f32_e32 v30, v30
	v_cvt_f16_f32_e32 v31, v31
	v_lshlrev_b32_e32 v25, 16, v25
	v_and_or_b32 v24, v24, s79, v25
	v_lshlrev_b32_e32 v27, 16, v27
	v_and_or_b32 v26, v26, s79, v27
	v_lshlrev_b32_e32 v29, 16, v29
	v_and_or_b32 v28, v28, s79, v29
	v_lshlrev_b32_e32 v31, 16, v31
	v_and_or_b32 v30, v30, s79, v31
	v_mov_b32_e32 v25, v26
	v_mov_b32_e32 v26, v28
	v_mov_b32_e32 v27, v30
	global_store_dwordx4 v57, v[24:27], s[76:77]
	s_add_u32 s76, s76, 0x10000
	s_addc_u32 s77, s77, 0
	v_cvt_f16_f32_e32 v32, v32
	v_cvt_f16_f32_e32 v33, v33
	v_cvt_f16_f32_e32 v34, v34
	v_cvt_f16_f32_e32 v35, v35
	v_cvt_f16_f32_e32 v36, v36
	v_cvt_f16_f32_e32 v37, v37
	v_cvt_f16_f32_e32 v38, v38
	v_cvt_f16_f32_e32 v39, v39
	v_lshlrev_b32_e32 v33, 16, v33
	v_and_or_b32 v32, v32, s79, v33
	v_lshlrev_b32_e32 v35, 16, v35
	v_and_or_b32 v34, v34, s79, v35
	v_lshlrev_b32_e32 v37, 16, v37
	v_and_or_b32 v36, v36, s79, v37
	v_lshlrev_b32_e32 v39, 16, v39
	v_and_or_b32 v38, v38, s79, v39
	v_mov_b32_e32 v33, v34
	v_mov_b32_e32 v34, v36
	v_mov_b32_e32 v35, v38
	global_store_dwordx4 v57, v[32:35], s[76:77]
	s_add_u32 s76, s76, 0x10000
	s_addc_u32 s77, s77, 0
	v_cvt_f16_f32_e32 v40, v40
	v_cvt_f16_f32_e32 v41, v41
	v_cvt_f16_f32_e32 v42, v42
	v_cvt_f16_f32_e32 v43, v43
	v_cvt_f16_f32_e32 v44, v44
	v_cvt_f16_f32_e32 v45, v45
	v_cvt_f16_f32_e32 v46, v46
	v_cvt_f16_f32_e32 v47, v47
	v_lshlrev_b32_e32 v41, 16, v41
	v_and_or_b32 v40, v40, s79, v41
	v_lshlrev_b32_e32 v43, 16, v43
	v_and_or_b32 v42, v42, s79, v43
	v_lshlrev_b32_e32 v45, 16, v45
	v_and_or_b32 v44, v44, s79, v45
	v_lshlrev_b32_e32 v47, 16, v47
	v_and_or_b32 v46, v46, s79, v47
	v_mov_b32_e32 v41, v42
	v_mov_b32_e32 v42, v44
	v_mov_b32_e32 v43, v46
	global_store_dwordx4 v57, v[40:43], s[76:77]
	s_add_u32 s76, s76, 0x10000
	s_addc_u32 s77, s77, 0
	v_cvt_f16_f32_e32 v48, v48
	v_cvt_f16_f32_e32 v49, v49
	v_cvt_f16_f32_e32 v50, v50
	v_cvt_f16_f32_e32 v51, v51
	v_cvt_f16_f32_e32 v52, v52
	v_cvt_f16_f32_e32 v53, v53
	v_cvt_f16_f32_e32 v54, v54
	v_cvt_f16_f32_e32 v55, v55
	v_lshlrev_b32_e32 v49, 16, v49
	v_and_or_b32 v48, v48, s79, v49
	v_lshlrev_b32_e32 v51, 16, v51
	v_and_or_b32 v50, v50, s79, v51
	v_lshlrev_b32_e32 v53, 16, v53
	v_and_or_b32 v52, v52, s79, v53
	v_lshlrev_b32_e32 v55, 16, v55
	v_and_or_b32 v54, v54, s79, v55
	v_mov_b32_e32 v49, v50
	v_mov_b32_e32 v50, v52
	v_mov_b32_e32 v51, v54
	global_store_dwordx4 v57, v[48:51], s[76:77]
	v_add_co_u32_e32 v26, vcc, 0x1000, v18
	s_waitcnt lgkmcnt(0)
	s_nop 0
	v_addc_co_u32_e32 v27, vcc, 0, v19, vcc
	v_add_co_u32_e32 v28, vcc, 0x2000, v18
	s_barrier
	s_nop 0
	v_addc_co_u32_e32 v29, vcc, 0, v19, vcc
	v_add_co_u32_e32 v30, vcc, 0x3000, v18
	s_nop 1
	v_addc_co_u32_e32 v31, vcc, 0, v19, vcc
	v_add_co_u32_e32 v32, vcc, 0x4000, v18
	global_load_dwordx2 v[24:25], v[18:19], off offset:512
	s_nop 0
	v_addc_co_u32_e32 v33, vcc, 0, v19, vcc
	v_add_co_u32_e32 v34, vcc, 0x5000, v18
	global_load_dwordx2 v[26:27], v[26:27], off offset:512
	s_nop 0
	global_load_dwordx2 v[28:29], v[28:29], off offset:512
	s_nop 0
	global_load_dwordx2 v[30:31], v[30:31], off offset:512
	s_nop 0
	global_load_dwordx2 v[32:33], v[32:33], off offset:512
	v_addc_co_u32_e32 v35, vcc, 0, v19, vcc
	v_add_co_u32_e32 v36, vcc, 0x6000, v18
	s_mov_b32 s2, 16
	s_nop 0
	v_addc_co_u32_e32 v37, vcc, 0, v19, vcc
	v_add_co_u32_e32 v38, vcc, 0x7000, v18
	s_nop 1
	v_addc_co_u32_e32 v39, vcc, 0, v19, vcc
	v_add_co_u32_e32 v40, vcc, 0x8000, v18
	s_nop 1
	v_addc_co_u32_e32 v41, vcc, 0, v19, vcc
	v_add_co_u32_e32 v42, vcc, 0x9000, v18
	global_load_dwordx2 v[34:35], v[34:35], off offset:512
	s_nop 0
	global_load_dwordx2 v[36:37], v[36:37], off offset:512
	s_nop 0
	global_load_dwordx2 v[38:39], v[38:39], off offset:512
	s_nop 0
	global_load_dwordx2 v[40:41], v[40:41], off offset:512
	v_addc_co_u32_e32 v43, vcc, 0, v19, vcc
	v_add_co_u32_e32 v44, vcc, 0xa000, v18
	s_nop 1
	v_addc_co_u32_e32 v45, vcc, 0, v19, vcc
	v_add_co_u32_e32 v46, vcc, 0xb000, v18
	s_nop 1
	v_addc_co_u32_e32 v47, vcc, 0, v19, vcc
	v_add_co_u32_e32 v48, vcc, 0xc000, v18
	s_nop 1
	v_addc_co_u32_e32 v49, vcc, 0, v19, vcc
	v_add_co_u32_e32 v50, vcc, 0xd000, v18
	global_load_dwordx2 v[42:43], v[42:43], off offset:512
	s_nop 0
	global_load_dwordx2 v[44:45], v[44:45], off offset:512
	s_nop 0
	global_load_dwordx2 v[46:47], v[46:47], off offset:512
	s_nop 0
	global_load_dwordx2 v[48:49], v[48:49], off offset:512
	v_addc_co_u32_e32 v51, vcc, 0, v19, vcc
	v_add_co_u32_e32 v52, vcc, 0xe000, v18
	s_nop 1
	v_addc_co_u32_e32 v53, vcc, 0, v19, vcc
	v_add_co_u32_e32 v54, vcc, 0xf000, v18
	s_nop 1
	v_addc_co_u32_e32 v55, vcc, 0, v19, vcc
	global_load_dwordx2 v[18:19], v[50:51], off offset:512
	s_nop 0
	global_load_dwordx2 v[50:51], v[52:53], off offset:512
	s_nop 0
	global_load_dwordx2 v[52:53], v[54:55], off offset:512
	s_nop 0
	global_load_dwordx2 v[22:23], v[22:23], off offset:512
	v_mov_b32_e32 v54, 0
	v_mov_b32_e32 v55, v54
.LBB0_292:
	s_add_i32 s4, s48, 0
	s_add_i32 s0, s4, 0x20400
	v_mov_b32_e32 v56, s0
	ds_read_b128 v[56:59], v56
	s_add_i32 s0, s4, 0x20410
	s_addk_i32 s48, 0x100
	s_add_i32 s2, s2, -4
	s_waitcnt vmcnt(0) lgkmcnt(0)
	v_pk_fma_f32 v[74:75], v[24:25], v[56:57], v[22:23] op_sel_hi:[1,0,1]
	s_nop 0
	v_pk_fma_f32 v[56:57], v[26:27], v[56:57], v[74:75] op_sel:[0,1,0]
	s_nop 0
	v_pk_fma_f32 v[56:57], v[28:29], v[58:59], v[56:57] op_sel_hi:[1,0,1]
	v_mov_b32_e32 v58, v59
	v_pk_fma_f32 v[74:75], v[30:31], v[58:59], v[56:57] op_sel_hi:[1,0,1]
	v_mov_b32_e32 v56, s0
	ds_read_b128 v[56:59], v56
	s_add_i32 s0, s4, 0x20420
	s_waitcnt lgkmcnt(0)
	v_pk_fma_f32 v[74:75], v[32:33], v[56:57], v[74:75] op_sel_hi:[1,0,1]
	s_nop 0
	v_pk_fma_f32 v[56:57], v[34:35], v[56:57], v[74:75] op_sel:[0,1,0]
	s_nop 0
	v_pk_fma_f32 v[56:57], v[36:37], v[58:59], v[56:57] op_sel_hi:[1,0,1]
	v_mov_b32_e32 v58, v59
	v_pk_fma_f32 v[74:75], v[38:39], v[58:59], v[56:57] op_sel_hi:[1,0,1]
	v_mov_b32_e32 v56, s0
	ds_read_b128 v[56:59], v56
	s_add_i32 s0, s4, 0x20430
	s_waitcnt lgkmcnt(0)
	v_pk_fma_f32 v[74:75], v[40:41], v[56:57], v[74:75] op_sel_hi:[1,0,1]
	s_nop 0
	v_pk_fma_f32 v[56:57], v[42:43], v[56:57], v[74:75] op_sel:[0,1,0]
	s_nop 0
	v_pk_fma_f32 v[56:57], v[44:45], v[58:59], v[56:57] op_sel_hi:[1,0,1]
	v_mov_b32_e32 v58, v59
	v_pk_fma_f32 v[74:75], v[46:47], v[58:59], v[56:57] op_sel_hi:[1,0,1]
	v_mov_b32_e32 v56, s0
	ds_read_b128 v[56:59], v56
	s_waitcnt lgkmcnt(0)
	v_pk_fma_f32 v[74:75], v[48:49], v[56:57], v[74:75] op_sel_hi:[1,0,1]
	s_nop 0
	v_pk_fma_f32 v[56:57], v[18:19], v[56:57], v[74:75] op_sel:[0,1,0]
	s_nop 0
	v_pk_fma_f32 v[56:57], v[50:51], v[58:59], v[56:57] op_sel_hi:[1,0,1]
	v_mov_b32_e32 v58, v59
	v_pk_fma_f32 v[56:57], v[52:53], v[58:59], v[56:57] op_sel_hi:[1,0,1]
	s_nop 0
	v_min_f32_e32 v58, 0, v56
	v_mul_f32_e64 v56, |v56|, s59
	v_exp_f32_e32 v56, v56
	s_nop 0
	v_add_f32_e32 v56, 1.0, v56
	v_cmp_gt_f32_e32 vcc, s3, v56
	s_nop 1
	v_cndmask_b32_e64 v59, 0, 32, vcc
	v_ldexp_f32 v56, v56, v59
	v_log_f32_e32 v56, v56
	s_nop 0
	v_mul_f32_e32 v59, 0x3f317217, v56
	v_fma_f32 v59, v56, s33, -v59
	v_fmac_f32_e32 v59, 0x3377d1cf, v56
	v_fmac_f32_e32 v59, 0x3f317217, v56
	v_cmp_lt_f32_e64 s[0:1], |v56|, s88
	s_nop 1
	v_cndmask_b32_e64 v56, v56, v59, s[0:1]
	v_cndmask_b32_e32 v59, 0, v169, vcc
	v_sub_f32_e32 v56, v56, v59
	v_min_f32_e32 v59, 0, v57
	v_mul_f32_e64 v57, |v57|, s59
	v_exp_f32_e32 v57, v57
	s_nop 0
	v_add_f32_e32 v57, 1.0, v57
	v_cmp_gt_f32_e32 vcc, s3, v57
	s_nop 1
	v_cndmask_b32_e64 v73, 0, 32, vcc
	v_ldexp_f32 v57, v57, v73
	v_log_f32_e32 v57, v57
	s_nop 0
	v_mul_f32_e32 v73, 0x3f317217, v57
	v_fma_f32 v73, v57, s33, -v73
	v_fmac_f32_e32 v73, 0x3377d1cf, v57
	v_fmac_f32_e32 v73, 0x3f317217, v57
	v_cmp_lt_f32_e64 s[0:1], |v57|, s88
	s_nop 1
	v_cndmask_b32_e64 v57, v57, v73, s[0:1]
	v_cndmask_b32_e32 v73, 0, v169, vcc
	v_sub_f32_e32 v57, v57, v73
	v_pk_add_f32 v[56:57], v[58:59], v[56:57] neg_lo:[0,1] neg_hi:[0,1]
	v_add_u32_e32 v73, 0, v69
	v_pk_mul_f32 v[58:59], v[56:57], s[26:27] op_sel_hi:[1,0]
	v_add_u32_e32 v74, 0x10000, v73
	s_add_i32 s0, s4, 0x20440
	ds_write_b64 v74, v[58:59]
	v_pk_fma_f32 v[58:59], v[56:57], s[26:27], v[54:55] op_sel_hi:[1,0,1]
	v_mov_b32_e32 v54, s0
	ds_read_b128 v[54:57], v54
	s_add_i32 s0, s4, 0x20450
	v_add_u32_e32 v69, 0x800, v69
	s_waitcnt lgkmcnt(0)
	v_pk_fma_f32 v[74:75], v[24:25], v[54:55], v[22:23] op_sel_hi:[1,0,1]
	s_nop 0
	v_pk_fma_f32 v[54:55], v[26:27], v[54:55], v[74:75] op_sel:[0,1,0]
	s_nop 0
	v_pk_fma_f32 v[54:55], v[28:29], v[56:57], v[54:55] op_sel_hi:[1,0,1]
	v_mov_b32_e32 v56, v57
	v_pk_fma_f32 v[74:75], v[30:31], v[56:57], v[54:55] op_sel_hi:[1,0,1]
	v_mov_b32_e32 v54, s0
	ds_read_b128 v[54:57], v54
	s_add_i32 s0, s4, 0x20460
	s_waitcnt lgkmcnt(0)
	v_pk_fma_f32 v[74:75], v[32:33], v[54:55], v[74:75] op_sel_hi:[1,0,1]
	s_nop 0
	v_pk_fma_f32 v[54:55], v[34:35], v[54:55], v[74:75] op_sel:[0,1,0]
	s_nop 0
	v_pk_fma_f32 v[54:55], v[36:37], v[56:57], v[54:55] op_sel_hi:[1,0,1]
	v_mov_b32_e32 v56, v57
	v_pk_fma_f32 v[74:75], v[38:39], v[56:57], v[54:55] op_sel_hi:[1,0,1]
	v_mov_b32_e32 v54, s0
	ds_read_b128 v[54:57], v54
	s_add_i32 s0, s4, 0x20470
	s_waitcnt lgkmcnt(0)
	v_pk_fma_f32 v[74:75], v[40:41], v[54:55], v[74:75] op_sel_hi:[1,0,1]
	s_nop 0
	v_pk_fma_f32 v[54:55], v[42:43], v[54:55], v[74:75] op_sel:[0,1,0]
	s_nop 0
	v_pk_fma_f32 v[54:55], v[44:45], v[56:57], v[54:55] op_sel_hi:[1,0,1]
	v_mov_b32_e32 v56, v57
	v_pk_fma_f32 v[74:75], v[46:47], v[56:57], v[54:55] op_sel_hi:[1,0,1]
	v_mov_b32_e32 v54, s0
	ds_read_b128 v[54:57], v54
	s_waitcnt lgkmcnt(0)
	v_pk_fma_f32 v[74:75], v[48:49], v[54:55], v[74:75] op_sel_hi:[1,0,1]
	s_nop 0
	v_pk_fma_f32 v[54:55], v[18:19], v[54:55], v[74:75] op_sel:[0,1,0]
	s_nop 0
	v_pk_fma_f32 v[54:55], v[50:51], v[56:57], v[54:55] op_sel_hi:[1,0,1]
	v_mov_b32_e32 v56, v57
	v_pk_fma_f32 v[54:55], v[52:53], v[56:57], v[54:55] op_sel_hi:[1,0,1]
	s_nop 0
	v_min_f32_e32 v56, 0, v54
	v_mul_f32_e64 v54, |v54|, s59
	v_exp_f32_e32 v54, v54
	s_nop 0
	v_add_f32_e32 v54, 1.0, v54
	v_cmp_gt_f32_e32 vcc, s3, v54
	s_nop 1
	v_cndmask_b32_e64 v57, 0, 32, vcc
	v_ldexp_f32 v54, v54, v57
	v_log_f32_e32 v54, v54
	s_nop 0
	v_mul_f32_e32 v57, 0x3f317217, v54
	v_fma_f32 v57, v54, s33, -v57
	v_fmac_f32_e32 v57, 0x3377d1cf, v54
	v_fmac_f32_e32 v57, 0x3f317217, v54
	v_cmp_lt_f32_e64 s[0:1], |v54|, s88
	s_nop 1
	v_cndmask_b32_e64 v54, v54, v57, s[0:1]
	v_cndmask_b32_e32 v57, 0, v169, vcc
	v_sub_f32_e32 v54, v54, v57
	v_min_f32_e32 v57, 0, v55
	v_mul_f32_e64 v55, |v55|, s59
	v_exp_f32_e32 v55, v55
	s_nop 0
	v_add_f32_e32 v55, 1.0, v55
	v_cmp_gt_f32_e32 vcc, s3, v55
	s_nop 1
	v_cndmask_b32_e64 v74, 0, 32, vcc
	v_ldexp_f32 v55, v55, v74
	v_log_f32_e32 v55, v55
	s_nop 0
	v_mul_f32_e32 v74, 0x3f317217, v55
	v_fma_f32 v74, v55, s33, -v74
	v_fmac_f32_e32 v74, 0x3377d1cf, v55
	v_fmac_f32_e32 v74, 0x3f317217, v55
	v_cmp_lt_f32_e64 s[0:1], |v55|, s88
	s_nop 1
	v_cndmask_b32_e64 v55, v55, v74, s[0:1]
	v_cndmask_b32_e32 v74, 0, v169, vcc
	v_sub_f32_e32 v55, v55, v74
	v_pk_add_f32 v[54:55], v[56:57], v[54:55] neg_lo:[0,1] neg_hi:[0,1]
	v_add_u32_e32 v74, 0x10200, v73
	v_pk_mul_f32 v[56:57], v[54:55], s[26:27] op_sel_hi:[1,0]
	s_add_i32 s0, s4, 0x20480
	ds_write_b64 v74, v[56:57]
	v_pk_fma_f32 v[58:59], v[54:55], s[26:27], v[58:59] op_sel_hi:[1,0,1]
	v_mov_b32_e32 v54, s0
	ds_read_b128 v[54:57], v54
	s_add_i32 s0, s4, 0x20490
	s_waitcnt lgkmcnt(0)
	v_pk_fma_f32 v[74:75], v[24:25], v[54:55], v[22:23] op_sel_hi:[1,0,1]
	s_nop 0
	v_pk_fma_f32 v[54:55], v[26:27], v[54:55], v[74:75] op_sel:[0,1,0]
	s_nop 0
	v_pk_fma_f32 v[54:55], v[28:29], v[56:57], v[54:55] op_sel_hi:[1,0,1]
	v_mov_b32_e32 v56, v57
	v_pk_fma_f32 v[74:75], v[30:31], v[56:57], v[54:55] op_sel_hi:[1,0,1]
	v_mov_b32_e32 v54, s0
	ds_read_b128 v[54:57], v54
	s_add_i32 s0, s4, 0x204a0
	s_waitcnt lgkmcnt(0)
	v_pk_fma_f32 v[74:75], v[32:33], v[54:55], v[74:75] op_sel_hi:[1,0,1]
	s_nop 0
	v_pk_fma_f32 v[54:55], v[34:35], v[54:55], v[74:75] op_sel:[0,1,0]
	s_nop 0
	v_pk_fma_f32 v[54:55], v[36:37], v[56:57], v[54:55] op_sel_hi:[1,0,1]
	v_mov_b32_e32 v56, v57
	v_pk_fma_f32 v[74:75], v[38:39], v[56:57], v[54:55] op_sel_hi:[1,0,1]
	v_mov_b32_e32 v54, s0
	ds_read_b128 v[54:57], v54
	s_add_i32 s0, s4, 0x204b0
	s_waitcnt lgkmcnt(0)
	v_pk_fma_f32 v[74:75], v[40:41], v[54:55], v[74:75] op_sel_hi:[1,0,1]
	s_nop 0
	v_pk_fma_f32 v[54:55], v[42:43], v[54:55], v[74:75] op_sel:[0,1,0]
	s_nop 0
	v_pk_fma_f32 v[54:55], v[44:45], v[56:57], v[54:55] op_sel_hi:[1,0,1]
	v_mov_b32_e32 v56, v57
	v_pk_fma_f32 v[74:75], v[46:47], v[56:57], v[54:55] op_sel_hi:[1,0,1]
	v_mov_b32_e32 v54, s0
	ds_read_b128 v[54:57], v54
	s_waitcnt lgkmcnt(0)
	v_pk_fma_f32 v[74:75], v[48:49], v[54:55], v[74:75] op_sel_hi:[1,0,1]
	s_nop 0
	v_pk_fma_f32 v[54:55], v[18:19], v[54:55], v[74:75] op_sel:[0,1,0]
	s_nop 0
	v_pk_fma_f32 v[54:55], v[50:51], v[56:57], v[54:55] op_sel_hi:[1,0,1]
	v_mov_b32_e32 v56, v57
	v_pk_fma_f32 v[54:55], v[52:53], v[56:57], v[54:55] op_sel_hi:[1,0,1]
	s_nop 0
	v_min_f32_e32 v56, 0, v54
	v_mul_f32_e64 v54, |v54|, s59
	v_exp_f32_e32 v54, v54
	s_nop 0
	v_add_f32_e32 v54, 1.0, v54
	v_cmp_gt_f32_e32 vcc, s3, v54
	s_nop 1
	v_cndmask_b32_e64 v57, 0, 32, vcc
	v_ldexp_f32 v54, v54, v57
	v_log_f32_e32 v54, v54
	s_nop 0
	v_mul_f32_e32 v57, 0x3f317217, v54
	v_fma_f32 v57, v54, s33, -v57
	v_fmac_f32_e32 v57, 0x3377d1cf, v54
	v_fmac_f32_e32 v57, 0x3f317217, v54
	v_cmp_lt_f32_e64 s[0:1], |v54|, s88
	s_nop 1
	v_cndmask_b32_e64 v54, v54, v57, s[0:1]
	v_cndmask_b32_e32 v57, 0, v169, vcc
	v_sub_f32_e32 v54, v54, v57
	v_min_f32_e32 v57, 0, v55
	v_mul_f32_e64 v55, |v55|, s59
	v_exp_f32_e32 v55, v55
	s_nop 0
	v_add_f32_e32 v55, 1.0, v55
	v_cmp_gt_f32_e32 vcc, s3, v55
	s_nop 1
	v_cndmask_b32_e64 v74, 0, 32, vcc
	v_ldexp_f32 v55, v55, v74
	v_log_f32_e32 v55, v55
	s_nop 0
	v_mul_f32_e32 v74, 0x3f317217, v55
	v_fma_f32 v74, v55, s33, -v74
	v_fmac_f32_e32 v74, 0x3377d1cf, v55
	v_fmac_f32_e32 v74, 0x3f317217, v55
	v_cmp_lt_f32_e64 s[0:1], |v55|, s88
	s_nop 1
	v_cndmask_b32_e64 v55, v55, v74, s[0:1]
	v_cndmask_b32_e32 v74, 0, v169, vcc
	v_sub_f32_e32 v55, v55, v74
	v_pk_add_f32 v[54:55], v[56:57], v[54:55] neg_lo:[0,1] neg_hi:[0,1]
	v_add_u32_e32 v74, 0x10400, v73
	v_pk_mul_f32 v[56:57], v[54:55], s[26:27] op_sel_hi:[1,0]
	s_add_i32 s0, s4, 0x204c0
	ds_write_b64 v74, v[56:57]
	v_pk_fma_f32 v[58:59], v[54:55], s[26:27], v[58:59] op_sel_hi:[1,0,1]
	v_mov_b32_e32 v54, s0
	ds_read_b128 v[54:57], v54
	s_add_i32 s0, s4, 0x204d0
	v_add_u32_e32 v73, 0x10600, v73
	s_waitcnt lgkmcnt(0)
	v_pk_fma_f32 v[74:75], v[24:25], v[54:55], v[22:23] op_sel_hi:[1,0,1]
	s_nop 0
	v_pk_fma_f32 v[54:55], v[26:27], v[54:55], v[74:75] op_sel:[0,1,0]
	s_nop 0
	v_pk_fma_f32 v[54:55], v[28:29], v[56:57], v[54:55] op_sel_hi:[1,0,1]
	v_mov_b32_e32 v56, v57
	v_pk_fma_f32 v[74:75], v[30:31], v[56:57], v[54:55] op_sel_hi:[1,0,1]
	v_mov_b32_e32 v54, s0
	ds_read_b128 v[54:57], v54
	s_add_i32 s0, s4, 0x204e0
	s_waitcnt lgkmcnt(0)
	v_pk_fma_f32 v[74:75], v[32:33], v[54:55], v[74:75] op_sel_hi:[1,0,1]
	s_nop 0
	v_pk_fma_f32 v[54:55], v[34:35], v[54:55], v[74:75] op_sel:[0,1,0]
	s_nop 0
	v_pk_fma_f32 v[54:55], v[36:37], v[56:57], v[54:55] op_sel_hi:[1,0,1]
	v_mov_b32_e32 v56, v57
	v_pk_fma_f32 v[74:75], v[38:39], v[56:57], v[54:55] op_sel_hi:[1,0,1]
	v_mov_b32_e32 v54, s0
	ds_read_b128 v[54:57], v54
	s_add_i32 s0, s4, 0x204f0
	s_cmp_lg_u32 s2, 0
	s_waitcnt lgkmcnt(0)
	v_pk_fma_f32 v[74:75], v[40:41], v[54:55], v[74:75] op_sel_hi:[1,0,1]
	s_nop 0
	v_pk_fma_f32 v[54:55], v[42:43], v[54:55], v[74:75] op_sel:[0,1,0]
	s_nop 0
	v_pk_fma_f32 v[54:55], v[44:45], v[56:57], v[54:55] op_sel_hi:[1,0,1]
	v_mov_b32_e32 v56, v57
	v_pk_fma_f32 v[74:75], v[46:47], v[56:57], v[54:55] op_sel_hi:[1,0,1]
	v_mov_b32_e32 v54, s0
	ds_read_b128 v[54:57], v54
	s_waitcnt lgkmcnt(0)
	v_pk_fma_f32 v[74:75], v[48:49], v[54:55], v[74:75] op_sel_hi:[1,0,1]
	s_nop 0
	v_pk_fma_f32 v[54:55], v[18:19], v[54:55], v[74:75] op_sel:[0,1,0]
	s_nop 0
	v_pk_fma_f32 v[54:55], v[50:51], v[56:57], v[54:55] op_sel_hi:[1,0,1]
	v_mov_b32_e32 v56, v57
	v_pk_fma_f32 v[54:55], v[52:53], v[56:57], v[54:55] op_sel_hi:[1,0,1]
	s_nop 0
	v_min_f32_e32 v56, 0, v54
	v_mul_f32_e64 v54, |v54|, s59
	v_exp_f32_e32 v54, v54
	s_nop 0
	v_add_f32_e32 v54, 1.0, v54
	v_cmp_gt_f32_e32 vcc, s3, v54
	s_nop 1
	v_cndmask_b32_e64 v57, 0, 32, vcc
	v_ldexp_f32 v54, v54, v57
	v_log_f32_e32 v54, v54
	s_nop 0
	v_mul_f32_e32 v57, 0x3f317217, v54
	v_fma_f32 v57, v54, s33, -v57
	v_fmac_f32_e32 v57, 0x3377d1cf, v54
	v_fmac_f32_e32 v57, 0x3f317217, v54
	v_cmp_lt_f32_e64 s[0:1], |v54|, s88
	s_nop 1
	v_cndmask_b32_e64 v54, v54, v57, s[0:1]
	v_cndmask_b32_e32 v57, 0, v169, vcc
	v_sub_f32_e32 v54, v54, v57
	v_min_f32_e32 v57, 0, v55
	v_mul_f32_e64 v55, |v55|, s59
	v_exp_f32_e32 v55, v55
	s_nop 0
	v_add_f32_e32 v55, 1.0, v55
	v_cmp_gt_f32_e32 vcc, s3, v55
	s_nop 1
	v_cndmask_b32_e64 v74, 0, 32, vcc
	v_ldexp_f32 v55, v55, v74
	v_log_f32_e32 v55, v55
	s_nop 0
	v_mul_f32_e32 v74, 0x3f317217, v55
	v_fma_f32 v74, v55, s33, -v74
	v_fmac_f32_e32 v74, 0x3377d1cf, v55
	v_fmac_f32_e32 v74, 0x3f317217, v55
	v_cmp_lt_f32_e64 s[0:1], |v55|, s88
	s_nop 1
	v_cndmask_b32_e64 v55, v55, v74, s[0:1]
	v_cndmask_b32_e32 v74, 0, v169, vcc
	v_sub_f32_e32 v55, v55, v74
	v_pk_add_f32 v[54:55], v[56:57], v[54:55] neg_lo:[0,1] neg_hi:[0,1]
	s_nop 0
	v_pk_mul_f32 v[56:57], v[54:55], s[26:27] op_sel_hi:[1,0]
	v_pk_fma_f32 v[54:55], v[54:55], s[26:27], v[58:59] op_sel_hi:[1,0,1]
	ds_write_b64 v73, v[56:57]
	s_cbranch_scc1 .LBB0_292
	ds_write_b64 v72, v[54:55]
	s_waitcnt lgkmcnt(0)
	s_barrier
	ds_read2st64_b32 v[18:19], v71 offset1:2
	v_or_b32_e32 v0, 0x80, v0
	v_lshrrev_b32_e32 v0, 3, v0
	s_movk_i32 s0, 0xc000
	s_mov_b32 s1, 1
	s_waitcnt lgkmcnt(0)
	v_add_f32_e32 v18, 0, v18
	v_add_f32_e32 v22, v18, v19
	ds_read2st64_b32 v[18:19], v71 offset0:4 offset1:6
	v_cndmask_b32_e64 v23, 0, v22, s[44:45]
	s_waitcnt lgkmcnt(0)
	v_add_f32_e32 v22, v22, v18
	v_add_f32_e32 v18, v18, v23
	v_add_f32_e32 v18, v19, v18
	v_add_f32_e32 v22, v22, v19
	v_cndmask_b32_e64 v23, v23, v18, s[42:43]
	ds_read2st64_b32 v[18:19], v71 offset0:8 offset1:10
	s_waitcnt lgkmcnt(0)
	v_add_f32_e32 v22, v22, v18
	v_add_f32_e32 v18, v18, v23
	v_add_f32_e32 v18, v19, v18
	v_add_f32_e32 v22, v22, v19
	v_cndmask_b32_e64 v23, v23, v18, s[40:41]
	ds_read2st64_b32 v[18:19], v71 offset0:12 offset1:14
	s_waitcnt lgkmcnt(0)
	v_add_f32_e32 v22, v22, v18
	v_add_f32_e32 v18, v18, v23
	v_add_f32_e32 v18, v19, v18
	v_add_f32_e32 v22, v22, v19
	v_cndmask_b32_e64 v23, v23, v18, s[36:37]
	v_lshl_add_u64 v[18:19], s[12:13], 0, v[20:21]
	s_nop 1
	v_readfirstlane_b32 s76, v18
	v_readfirstlane_b32 s77, v19
	v_readlane_b32 s78, v252, 8
	s_lshr_b32 s79, s78, 7
	s_lshl_b32 s79, s79, 16
	s_and_b32 s78, s78, 64
	s_lshl_b32 s78, s78, 1
	s_add_i32 s78, s78, s79
	s_addk_i32 s78, 0x3800
	s_sub_u32 s76, s76, s78
	s_subb_u32 s77, s77, 0
.LBB0_294:
	v_add_u32_e32 v24, s0, v61
	v_add_u32_e32 v211, 0x10000, v24
	v_add_u32_e32 v20, 0x14000, v24
	ds_read_b32 v20, v20
	s_add_i32 s2, s1, -1
	s_and_b32 s4, s2, 2
	s_waitcnt lgkmcnt(0)
	v_add_f32_e32 v23, v23, v20
	v_cvt_f16_f32_e32 v25, v23
	v_add_co_u32_e32 v20, vcc, 0xffffd000, v18
	v_sub_f32_e32 v27, v22, v23
	s_nop 0
	v_addc_co_u32_e32 v21, vcc, -1, v19, vcc
	ds_write_b32 v211, v23 offset:16384
	v_bitop3_b32 v25, s2, v0, 2 bitop3:0x6c
	v_lshlrev_b32_e32 v25, 4, v25
	v_add3_u32 v25, v60, v25, s0
	ds_read_u16 v26, v25 offset:16384
	v_mul_f32_e32 v27, 0x3fb8aa3b, v27
	v_exp_f32_e32 v27, v27
	s_and_b32 s2, s1, 3
	s_waitcnt lgkmcnt(0)
	v_lshlrev_b32_e32 v26, 16, v26
	v_mul_f32_e32 v26, v27, v26
	v_bfe_u32 v27, v26, 16, 1
	v_add3_u32 v26, v26, v27, s90
	ds_write_b16_d16_hi v25, v26 offset:16384
	v_add_u32_e32 v25, 0x14200, v24
	ds_read_b32 v25, v25
	s_waitcnt lgkmcnt(0)
	v_add_f32_e32 v23, v23, v25
	v_cvt_f16_f32_e32 v25, v23
	ds_write_b32 v211, v23 offset:16896
	v_bitop3_b32 v20, s4, v0, 4 bitop3:0x36
	v_lshlrev_b32_e32 v20, 4, v20
	v_add3_u32 v20, v60, v20, s0
	ds_read_u16 v21, v20 offset:16896
	v_sub_f32_e32 v25, v22, v23
	v_mul_f32_e32 v25, 0x3fb8aa3b, v25
	v_exp_f32_e32 v25, v25
	s_waitcnt lgkmcnt(0)
	v_lshlrev_b32_e32 v21, 16, v21
	v_mul_f32_e32 v21, v25, v21
	v_bfe_u32 v25, v21, 16, 1
	v_add3_u32 v21, v21, v25, s90
	ds_write_b16_d16_hi v20, v21 offset:16896
	v_add_u32_e32 v20, 0x14400, v24
	ds_read_b32 v20, v20
	s_waitcnt lgkmcnt(0)
	v_add_f32_e32 v23, v23, v20
	v_cvt_f16_f32_e32 v25, v23
	v_add_co_u32_e32 v20, vcc, s91, v18
	v_sub_f32_e32 v27, v22, v23
	s_nop 0
	v_addc_co_u32_e32 v21, vcc, -1, v19, vcc
	ds_write_b32 v211, v23 offset:17408
	v_bitop3_b32 v25, s4, v0, 8 bitop3:0x36
	v_lshlrev_b32_e32 v25, 4, v25
	v_add3_u32 v25, v60, v25, s0
	ds_read_u16 v26, v25 offset:17408
	v_mul_f32_e32 v27, 0x3fb8aa3b, v27
	v_exp_f32_e32 v27, v27
	s_waitcnt lgkmcnt(0)
	v_lshlrev_b32_e32 v26, 16, v26
	v_mul_f32_e32 v26, v27, v26
	v_bfe_u32 v27, v26, 16, 1
	v_add3_u32 v26, v26, v27, s90
	ds_write_b16_d16_hi v25, v26 offset:17408
	v_add_u32_e32 v25, 0x14600, v24
	ds_read_b32 v25, v25
	s_waitcnt lgkmcnt(0)
	v_add_f32_e32 v23, v23, v25
	v_cvt_f16_f32_e32 v25, v23
	ds_write_b32 v211, v23 offset:17920
	v_bitop3_b32 v20, s4, v0, 12 bitop3:0x36
	v_lshlrev_b32_e32 v20, 4, v20
	v_add3_u32 v20, v60, v20, s0
	ds_read_u16 v21, v20 offset:17920
	v_sub_f32_e32 v25, v22, v23
	v_mul_f32_e32 v25, 0x3fb8aa3b, v25
	v_exp_f32_e32 v25, v25
	s_waitcnt lgkmcnt(0)
	v_lshlrev_b32_e32 v21, 16, v21
	v_mul_f32_e32 v21, v25, v21
	v_bfe_u32 v25, v21, 16, 1
	v_add3_u32 v21, v21, v25, s90
	ds_write_b16_d16_hi v20, v21 offset:17920
	v_add_u32_e32 v20, 0x14800, v24
	ds_read_b32 v20, v20
	s_waitcnt lgkmcnt(0)
	v_add_f32_e32 v23, v23, v20
	v_cvt_f16_f32_e32 v25, v23
	v_add_co_u32_e32 v20, vcc, s92, v18
	s_nop 1
	v_addc_co_u32_e32 v21, vcc, -1, v19, vcc
	ds_write_b32 v211, v23 offset:18432
	v_bitop3_b32 v20, s1, v0, 3 bitop3:0x6c
	v_lshlrev_b32_e32 v20, 4, v20
	v_add3_u32 v20, v60, v20, s0
	ds_read_u16 v21, v20 offset:18432
	v_sub_f32_e32 v25, v22, v23
	v_mul_f32_e32 v25, 0x3fb8aa3b, v25
	v_exp_f32_e32 v25, v25
	s_add_i32 s1, s1, 2
	s_waitcnt lgkmcnt(0)
	v_lshlrev_b32_e32 v21, 16, v21
	v_mul_f32_e32 v21, v25, v21
	v_bfe_u32 v25, v21, 16, 1
	v_add3_u32 v21, v21, v25, s90
	ds_write_b16_d16_hi v20, v21 offset:18432
	v_add_u32_e32 v20, 0x14a00, v24
	ds_read_b32 v20, v20
	s_waitcnt lgkmcnt(0)
	v_add_f32_e32 v20, v23, v20
	v_cvt_f16_f32_e32 v21, v20
	v_sub_f32_e32 v25, v22, v20
	v_mul_f32_e32 v25, 0x3fb8aa3b, v25
	v_exp_f32_e32 v25, v25
	ds_write_b32 v211, v20 offset:18944
	v_bitop3_b32 v21, s2, v0, 4 bitop3:0x36
	v_lshlrev_b32_e32 v21, 4, v21
	v_add3_u32 v21, v60, v21, s0
	ds_read_u16 v23, v21 offset:18944
	s_waitcnt lgkmcnt(0)
	v_lshlrev_b32_e32 v23, 16, v23
	v_mul_f32_e32 v23, v25, v23
	v_bfe_u32 v25, v23, 16, 1
	v_add3_u32 v23, v23, v25, s90
	ds_write_b16_d16_hi v21, v23 offset:18944
	v_add_u32_e32 v21, 0x14c00, v24
	ds_read_b32 v21, v21
	s_waitcnt lgkmcnt(0)
	v_add_f32_e32 v20, v20, v21
	v_cvt_f16_f32_e32 v21, v20
	v_sub_f32_e32 v25, v22, v20
	v_mul_f32_e32 v25, 0x3fb8aa3b, v25
	v_exp_f32_e32 v25, v25
	ds_write_b32 v211, v20 offset:19456
	v_bitop3_b32 v21, s2, v0, 8 bitop3:0x36
	v_lshlrev_b32_e32 v21, 4, v21
	v_add3_u32 v21, v60, v21, s0
	ds_read_u16 v23, v21 offset:19456
	s_waitcnt lgkmcnt(0)
	v_lshlrev_b32_e32 v23, 16, v23
	v_mul_f32_e32 v23, v25, v23
	v_bfe_u32 v25, v23, 16, 1
	v_add3_u32 v23, v23, v25, s90
	ds_write_b16_d16_hi v21, v23 offset:19456
	v_add_u32_e32 v21, 0x14e00, v24
	ds_read_b32 v21, v21
	s_waitcnt lgkmcnt(0)
	v_add_f32_e32 v23, v20, v21
	v_cvt_f16_f32_e32 v20, v23
	v_sub_f32_e32 v24, v22, v23
	v_mul_f32_e32 v24, 0x3fb8aa3b, v24
	v_exp_f32_e32 v24, v24
	ds_write_b32 v211, v23 offset:19968
	v_bitop3_b32 v20, s2, v0, 12 bitop3:0x36
	v_lshlrev_b32_e32 v20, 4, v20
	v_add3_u32 v20, v60, v20, s0
	ds_read_u16 v21, v20 offset:19968
	s_addk_i32 s0, 0x1000
	v_lshl_add_u64 v[18:19], v[18:19], 0, s[66:67]
	s_cmp_lg_u32 s0, 0
	s_waitcnt lgkmcnt(0)
	v_lshlrev_b32_e32 v21, 16, v21
	v_mul_f32_e32 v21, v24, v21
	v_bfe_u32 v24, v21, 16, 1
	v_add3_u32 v21, v21, v24, s90
	ds_write_b16_d16_hi v20, v21 offset:19968
	s_cbranch_scc1 .LBB0_294
	s_and_saveexec_b64 s[0:1], s[38:39]
	s_cbranch_execz .LBB0_297
	v_mul_f32_e32 v0, 0x3fb8aa3b, v22
	v_exp_f32_e32 v0, v0
	global_store_dword v70, v0, s[16:17] offset:512
.LBB0_297:
	s_or_b64 exec, exec, s[0:1]
	s_waitcnt lgkmcnt(0)
	s_barrier
	v_mbcnt_lo_u32_b32 v58, -1, 0
	v_mbcnt_hi_u32_b32 v58, -1, v58
	v_readlane_b32 s78, v252, 8
	s_mov_b32 s79, 0xffff
	v_add_u32_e32 v58, s78, v58
	v_lshlrev_b32_e32 v56, 5, v58
	v_add_u32_e32 v56, 0x10000, v56
	ds_read_b128 v[24:27], v56 offset:0
	ds_read_b128 v[28:31], v56 offset:16
	ds_read_b128 v[32:35], v56 offset:16384
	ds_read_b128 v[36:39], v56 offset:16400
	ds_read_b128 v[40:43], v56 offset:32768
	ds_read_b128 v[44:47], v56 offset:32784
	ds_read_b128 v[48:51], v56 offset:49152
	ds_read_b128 v[52:55], v56 offset:49168
	v_lshrrev_b32_e32 v57, 4, v58
	v_lshlrev_b32_e32 v57, 11, v57
	v_and_b32_e32 v58, 15, v58
	v_lshl_add_u32 v57, v58, 4, v57
	s_waitcnt lgkmcnt(0)
	s_barrier
	v_cvt_f16_f32_e32 v24, v24
	v_cvt_f16_f32_e32 v25, v25
	v_cvt_f16_f32_e32 v26, v26
	v_cvt_f16_f32_e32 v27, v27
	v_cvt_f16_f32_e32 v28, v28
	v_cvt_f16_f32_e32 v29, v29
	v_cvt_f16_f32_e32 v30, v30
	v_cvt_f16_f32_e32 v31, v31
	v_lshlrev_b32_e32 v25, 16, v25
	v_and_or_b32 v24, v24, s79, v25
	v_lshlrev_b32_e32 v27, 16, v27
	v_and_or_b32 v26, v26, s79, v27
	v_lshlrev_b32_e32 v29, 16, v29
	v_and_or_b32 v28, v28, s79, v29
	v_lshlrev_b32_e32 v31, 16, v31
	v_and_or_b32 v30, v30, s79, v31
	v_mov_b32_e32 v25, v26
	v_mov_b32_e32 v26, v28
	v_mov_b32_e32 v27, v30
	global_store_dwordx4 v57, v[24:27], s[76:77]
	s_add_u32 s76, s76, 0x10000
	s_addc_u32 s77, s77, 0
	v_cvt_f16_f32_e32 v32, v32
	v_cvt_f16_f32_e32 v33, v33
	v_cvt_f16_f32_e32 v34, v34
	v_cvt_f16_f32_e32 v35, v35
	v_cvt_f16_f32_e32 v36, v36
	v_cvt_f16_f32_e32 v37, v37
	v_cvt_f16_f32_e32 v38, v38
	v_cvt_f16_f32_e32 v39, v39
	v_lshlrev_b32_e32 v33, 16, v33
	v_and_or_b32 v32, v32, s79, v33
	v_lshlrev_b32_e32 v35, 16, v35
	v_and_or_b32 v34, v34, s79, v35
	v_lshlrev_b32_e32 v37, 16, v37
	v_and_or_b32 v36, v36, s79, v37
	v_lshlrev_b32_e32 v39, 16, v39
	v_and_or_b32 v38, v38, s79, v39
	v_mov_b32_e32 v33, v34
	v_mov_b32_e32 v34, v36
	v_mov_b32_e32 v35, v38
	global_store_dwordx4 v57, v[32:35], s[76:77]
	s_add_u32 s76, s76, 0x10000
	s_addc_u32 s77, s77, 0
	v_cvt_f16_f32_e32 v40, v40
	v_cvt_f16_f32_e32 v41, v41
	v_cvt_f16_f32_e32 v42, v42
	v_cvt_f16_f32_e32 v43, v43
	v_cvt_f16_f32_e32 v44, v44
	v_cvt_f16_f32_e32 v45, v45
	v_cvt_f16_f32_e32 v46, v46
	v_cvt_f16_f32_e32 v47, v47
	v_lshlrev_b32_e32 v41, 16, v41
	v_and_or_b32 v40, v40, s79, v41
	v_lshlrev_b32_e32 v43, 16, v43
	v_and_or_b32 v42, v42, s79, v43
	v_lshlrev_b32_e32 v45, 16, v45
	v_and_or_b32 v44, v44, s79, v45
	v_lshlrev_b32_e32 v47, 16, v47
	v_and_or_b32 v46, v46, s79, v47
	v_mov_b32_e32 v41, v42
	v_mov_b32_e32 v42, v44
	v_mov_b32_e32 v43, v46
	global_store_dwordx4 v57, v[40:43], s[76:77]
	s_add_u32 s76, s76, 0x10000
	s_addc_u32 s77, s77, 0
	v_cvt_f16_f32_e32 v48, v48
	v_cvt_f16_f32_e32 v49, v49
	v_cvt_f16_f32_e32 v50, v50
	v_cvt_f16_f32_e32 v51, v51
	v_cvt_f16_f32_e32 v52, v52
	v_cvt_f16_f32_e32 v53, v53
	v_cvt_f16_f32_e32 v54, v54
	v_cvt_f16_f32_e32 v55, v55
	v_lshlrev_b32_e32 v49, 16, v49
	v_and_or_b32 v48, v48, s79, v49
	v_lshlrev_b32_e32 v51, 16, v51
	v_and_or_b32 v50, v50, s79, v51
	v_lshlrev_b32_e32 v53, 16, v53
	v_and_or_b32 v52, v52, s79, v53
	v_lshlrev_b32_e32 v55, 16, v55
	v_and_or_b32 v54, v54, s79, v55
	v_mov_b32_e32 v49, v50
	v_mov_b32_e32 v50, v52
	v_mov_b32_e32 v51, v54
	global_store_dwordx4 v57, v[48:51], s[76:77]
	v_lshrrev_b32_e32 v18, 4, v68
	v_bfe_u32 v0, v63, 2, 2
	v_lshl_or_b32 v19, v18, 3, v0
	v_bfe_u32 v22, v63, 1, 1
	v_lshrrev_b32_e32 v0, 3, v68
	v_lshl_or_b32 v23, s46, 2, v22
	v_and_b32_e32 v24, 12, v63
	v_and_b32_e32 v25, 2, v0
	v_or_b32_e32 v26, v25, v24
	v_bitop3_b32 v37, v25, v23, v24 bitop3:0x36
	v_lshlrev_b32_e32 v119, 4, v37
	v_bitop3_b32 v37, v26, v23, 1 bitop3:0x36
	v_lshrrev_b32_e32 v21, 1, v63
	v_lshlrev_b32_e32 v120, 4, v37
	v_or_b32_e32 v37, 2, v23
	v_bitop3_b32 v23, v23, v26, 2 bitop3:0x36
	v_lshlrev_b32_e32 v121, 4, v23
	v_bitop3_b32 v23, v26, v37, 1 bitop3:0x36
	v_bitop3_b32 v21, v26, v21, 1 bitop3:0x72
	v_lshlrev_b32_e32 v122, 4, v23
	v_or_b32_e32 v23, v26, v22
	v_lshlrev_b32_e32 v126, 4, v21
	v_or_b32_e32 v21, 2, v22
	v_lshlrev_b32_e32 v125, 4, v23
	v_bitop3_b32 v23, v25, v21, v24 bitop3:0x36
	v_bitop3_b32 v21, v26, v21, 1 bitop3:0x36
	v_lshlrev_b32_e32 v128, 4, v21
	v_or_b32_e32 v21, 4, v22
	v_lshlrev_b32_e32 v127, 4, v23
	v_bitop3_b32 v23, v25, v21, v24 bitop3:0x36
	v_bitop3_b32 v21, v26, v21, 1 bitop3:0x36
	v_lshlrev_b32_e32 v130, 4, v21
	v_or_b32_e32 v21, 6, v22
	v_lshlrev_b32_e32 v129, 4, v23
	v_bitop3_b32 v23, v25, v21, v24 bitop3:0x36
	v_bitop3_b32 v21, v26, v21, 1 bitop3:0x36
	v_lshlrev_b32_e32 v132, 4, v21
	v_or_b32_e32 v21, 8, v22
	s_lshl_b32 s0, s49, 22
	v_lshlrev_b32_e32 v131, 4, v23
	v_bitop3_b32 v23, v25, v21, v24 bitop3:0x36
	v_bitop3_b32 v21, v26, v21, 1 bitop3:0x36
	v_and_b32_e32 v20, 15, v63
	s_add_i32 s4, s0, 0x5900000
	s_lshl_b64 s[0:1], s[20:21], 9
	v_lshlrev_b32_e32 v134, 4, v21
	v_or_b32_e32 v21, 10, v22
	s_add_u32 s2, s50, 0x2c80
	s_add_i32 s5, 0, 0x10000
	v_or_b32_e32 v106, s0, v20
	v_mov_b32_e32 v107, s1
	s_lshl_b64 s[0:1], s[20:21], 17
	v_lshlrev_b32_e32 v133, 4, v23
	v_bitop3_b32 v23, v25, v21, v24 bitop3:0x36
	v_bitop3_b32 v21, v26, v21, 1 bitop3:0x36
	s_cmp_lt_u32 s47, 64
	v_lshlrev_b32_e32 v136, 4, v21
	v_or_b32_e32 v21, 12, v22
	s_cselect_b64 s[16:17], -1, 0
	s_cmp_eq_u32 s46, 1
	v_lshlrev_b32_e32 v135, 4, v23
	v_bitop3_b32 v23, v25, v21, v24 bitop3:0x36
	v_bitop3_b32 v21, v26, v21, 1 bitop3:0x36
	s_cselect_b64 s[72:73], -1, 0
	s_cmp_eq_u32 s46, 2
	v_lshlrev_b32_e32 v138, 4, v21
	v_or_b32_e32 v21, 14, v22
	v_and_b32_e32 v0, 8, v64
	s_cselect_b64 s[64:65], -1, 0
	s_cmp_eq_u32 s46, 3
	v_bitop3_b32 v22, v25, v21, v24 bitop3:0x36
	v_bitop3_b32 v21, v26, v21, 1 bitop3:0x36
	v_add_u32_e32 v27, 0, v0
	v_add_u32_e32 v28, s5, v0
	v_and_b32_e32 v0, 48, v68
	v_lshlrev_b32_e32 v29, 2, v62
	v_lshlrev_b32_e32 v31, 2, v65
	v_lshlrev_b32_e32 v33, 2, v66
	v_lshlrev_b32_e32 v35, 2, v67
	s_cselect_b64 s[74:75], -1, 0
	s_cmp_eq_u32 s46, 4
	v_lshlrev_b32_e32 v140, 4, v21
	v_or_b32_e32 v21, 32, v19
	v_lshl_add_u64 v[108:109], s[52:53], 0, v[0:1]
	v_lshlrev_b32_e32 v0, 3, v18
	v_and_b32_e32 v29, 12, v29
	v_bfe_u32 v30, v62, 2, 2
	v_and_b32_e32 v31, 12, v31
	v_bfe_u32 v32, v65, 2, 2
	v_and_b32_e32 v33, 12, v33
	v_bfe_u32 v34, v66, 2, 2
	v_and_b32_e32 v35, 12, v35
	v_bfe_u32 v36, v67, 2, 2
	s_cselect_b64 s[76:77], -1, 0
	s_cmp_eq_u32 s46, 5
	v_lshlrev_b32_e32 v139, 4, v22
	v_lshl_add_u32 v141, v21, 9, v27
	v_or_b32_e32 v22, 36, v19
	v_lshl_add_u32 v143, v21, 8, v28
	v_or_b32_e32 v21, 64, v19
	v_lshl_or_b32 v18, s46, 5, v0
	v_bitop3_b32 v29, v29, v20, v30 bitop3:0x36
	v_bitop3_b32 v31, v31, v20, v32 bitop3:0x36
	v_bitop3_b32 v33, v33, v20, v34 bitop3:0x36
	v_bitop3_b32 v35, v35, v20, v36 bitop3:0x36
	v_lshl_add_u32 v117, v19, 9, v27
	v_or_b32_e32 v36, 4, v19
	v_lshl_add_u32 v123, v19, 8, v28
	s_cselect_b64 s[78:79], -1, 0
	s_cmp_eq_u32 s46, 6
	v_lshl_add_u32 v142, v22, 9, v27
	v_lshl_add_u32 v144, v22, 8, v28
	v_lshl_add_u32 v145, v21, 9, v27
	v_or_b32_e32 v22, 0x44, v19
	v_lshl_add_u32 v147, v21, 8, v28
	v_or_b32_e32 v21, 0x60, v19
	v_or_b32_e32 v19, 0x64, v19
	v_lshlrev_b32_e32 v0, 8, v62
	v_lshl_add_u32 v29, v29, 4, s5
	v_lshlrev_b32_e32 v30, 8, v65
	v_lshl_add_u32 v31, v31, 4, s5
	v_lshlrev_b32_e32 v32, 8, v66
	v_lshl_add_u32 v33, v33, 4, s5
	v_lshlrev_b32_e32 v34, 8, v67
	v_lshl_add_u32 v35, v35, 4, s5
	s_cselect_b64 s[80:81], -1, 0
	s_cmp_eq_u32 s46, 7
	v_lshl_add_u32 v150, v19, 9, v27
	v_lshl_add_u32 v152, v19, 8, v28
	v_ashrrev_i32_e32 v19, 31, v18
	v_lshl_add_u32 v118, v36, 9, v27
	v_lshl_add_u32 v124, v36, 8, v28
	v_lshlrev_b32_e32 v137, 4, v23
	s_cselect_b64 s[82:83], -1, 0
	v_lshl_add_u32 v146, v22, 9, v27
	v_lshl_add_u32 v148, v22, 8, v28
	v_lshl_add_u32 v149, v21, 9, v27
	v_lshl_add_u32 v151, v21, 8, v28
	v_lshl_add_u64 v[110:111], v[18:19], 1, s[10:11]
	v_lshlrev_b32_e32 v112, 8, v20
	v_mov_b32_e32 v113, v1
	s_mov_b64 s[84:85], 0
	v_add_u32_e32 v153, v29, v0
	v_add_u32_e32 v154, v31, v30
	v_add_u32_e32 v155, v33, v32
	v_add_u32_e32 v156, v35, v34
	s_mov_b64 s[86:87], 0
	s_waitcnt lgkmcnt(0)
	s_barrier
	s_branch .LBB0_299
